# deferred weight conversion: 1280 items per barrier (waves 1-5), so only the first 9 grid barriers carry conversion work
# baseline (speedup 1.0000x reference)
; __device__ __forceinline__ void prologue(const Args& a, LAS unsigned char* lds, int vcu, int G, int wave, int lane, int tid) {
;     ...
;     for (int it = gw; it < NITEMS; it += NGW) {
;         int r = it;
;         if (r < 2 * I_QKV) { const int l = r / I_QKV; r -= l * I_QKV; xpose_item(a.in[4] + (size_t)l * 1024 * 3072, 1024, 3072, (bf16*)(ws + WS_WQKV) + (size_t)l * 3072 * 1024, nmix + (l ? 3 : 0) * 1024, 4, scr, r, lane); continue; } r -= 2 * I_QKV;
;         if (r < 2 * I_SQ) { const int l = r / I_SQ; r -= l * I_SQ; xpose_item(a.in[5] + (size_t)l * 1024 * 1024, 1024, 1024, (bf16*)(ws + WS_WO) + (size_t)l * 1024 * 1024, nullptr, 4, scr, r, lane); continue; } r -= 2 * I_SQ;
;         if (r < 4 * I_POOL) { const int g = r / I_POOL; r -= g * I_POOL; xpose_item(a.in[6] + (size_t)g * 65536, 256, 256, (bf16*)(ws + WS_WPOOL) + (size_t)g * 65536, nullptr, 4, scr, r, lane); continue; } r -= 4 * I_POOL;
;         if (r < I_QKV) { xpose_item(a.in[8], 1024, 3072, (bf16*)(ws + WS_WCI), nmix + 2 * 1024, 1, scr, r, lane); continue; } r -= I_QKV;
;         if (r < I_SQ) { xpose_item(a.in[10], 1024, 1024, (bf16*)(ws + WS_WCO), nullptr, 4, scr, r, lane); continue; } r -= I_SQ;
;         if (r < 4 * I_UP) { const int l = r / I_UP; r -= l * I_UP; xpose_item(a.in[11] + (size_t)l * 1024 * 4096, 1024, 4096, (bf16*)(ws + WS_WUP) + (size_t)l * 4096 * 1024, nmlp + l * 1024, 4, scr, r, lane); continue; } r -= 4 * I_UP;
;         { const int l = r / I_DN; r -= l * I_DN; xpose_item(a.in[12] + (size_t)l * 4096 * 1024, 4096, 1024, (bf16*)(ws + WS_WDN) + (size_t)l * 1024 * 4096, nullptr, 4, scr, r, lane); }
.Lmy_items:
	s_mov_b64 exec, -1
	v_readfirstlane_b32 s3, v0
	s_lshr_b32 s3, s3, 6
	s_cmp_gt_u32 s3, 5
	s_cbranch_scc1 .LBB0_633
	v_writelane_b32 v200, s0, 0
	v_writelane_b32 v200, s1, 1
	v_writelane_b32 v200, s2, 2
	v_writelane_b32 v200, s3, 3
	v_writelane_b32 v200, s4, 4
	v_writelane_b32 v200, s5, 5
	v_writelane_b32 v200, s6, 6
	v_writelane_b32 v200, s7, 7
	v_writelane_b32 v200, s8, 8
	v_writelane_b32 v200, s9, 9
	v_writelane_b32 v200, s10, 10
	v_writelane_b32 v200, s11, 11
	v_writelane_b32 v200, s12, 12
	v_writelane_b32 v200, s13, 13
	v_writelane_b32 v200, s14, 14
	v_writelane_b32 v200, s15, 15
	v_writelane_b32 v200, s16, 16
	v_writelane_b32 v200, s17, 17
	v_writelane_b32 v200, s18, 18
	v_writelane_b32 v200, s19, 19
	v_writelane_b32 v200, s68, 20
	v_writelane_b32 v200, s69, 21
	v_writelane_b32 v200, s70, 22
	v_writelane_b32 v200, s71, 23
	v_writelane_b32 v200, s72, 24
	v_writelane_b32 v200, s73, 25
	v_writelane_b32 v200, s74, 26
	v_writelane_b32 v200, s75, 27
	v_writelane_b32 v200, s76, 28
	v_writelane_b32 v200, s77, 29
	v_writelane_b32 v200, s78, 30
	v_writelane_b32 v200, s79, 31
	v_writelane_b32 v200, s80, 32
	v_writelane_b32 v200, s81, 33
	v_writelane_b32 v200, s82, 34
	v_writelane_b32 v200, s83, 35
	v_writelane_b32 v200, s86, 36
	s_add_i32 s2, s66, -1
	s_add_i32 s4, s66, -2
	s_cmp_gt_u32 s66, 8
	s_cselect_b32 s2, s4, s2
	s_add_i32 s5, s3, -1
	s_lshl_b32 s5, s5, 8
	v_readlane_b32 s6, v255, 47
	s_lshr_b32 s7, s6, 3
	s_add_i32 s5, s5, s7
	s_cmp_ge_u32 s5, 1280
	s_cbranch_scc1 .Lmy_items_restore
	s_mul_i32 s2, s2, 1280
	s_add_i32 s2, s2, s5
	s_cmp_ge_u32 s2, 10560
	s_cbranch_scc1 .Lmy_items_restore
	s_mov_b32 s4, 1536
	s_cmp_ge_u32 s2, 256
	s_cselect_b32 s4, 2880, s4
	s_cmp_ge_u32 s2, 1280
	s_cselect_b32 s4, 5952, s4
	s_cmp_ge_u32 s2, 2304
	s_cselect_b32 s4, -256, s4
	s_cmp_ge_u32 s2, 2368
	s_cselect_b32 s4, 1792, s4
	s_cmp_ge_u32 s2, 3392
	s_cselect_b32 s4, 4864, s4
	s_cmp_ge_u32 s2, 4416
	s_cselect_b32 s4, -2304, s4
	s_cmp_ge_u32 s2, 5184
	s_cselect_b32 s4, -2304, s4
	s_cmp_ge_u32 s2, 5440
	s_cselect_b32 s4, -256, s4
	s_cmp_ge_u32 s2, 6464
	s_cselect_b32 s4, 2816, s4
	s_cmp_ge_u32 s2, 7488
	s_cselect_b32 s4, -6720, s4
	s_cmp_ge_u32 s2, 8256
	s_cselect_b32 s4, -6464, s4
	s_cmp_ge_u32 s2, 8512
	s_cselect_b32 s4, -2304, s4
	s_cmp_ge_u32 s2, 9536
	s_cselect_b32 s4, 768, s4
	s_add_i32 s19, s2, s4
	v_mov_b32_e32 v221, v0
	v_readlane_b32 s65, v253, 2
	s_mov_b32 s70, s3
	s_mov_b32 s85, s6
	v_readlane_b32 s28, v255, 48
	s_add_i32 s0, s70, s85
	s_sub_i32 s19, s19, s0
	s_lshl_b32 s12, s65, 3
	v_and_b32_e32 v2, 63, v221
	v_lshlrev_b32_e32 v66, 2, v2
	v_lshlrev_b32_e32 v68, 3, v2
	s_mov_b32 s32, 1
	s_branch .Lmy_p0_init
